# v7 without the retention wave remap (epilogue prefetches + retention load hoists and LDS read pipelining only): bit-stable outputs
# baseline (speedup 1.0000x reference)
; #define LAS __attribute__((address_space(3)))
; __device__ __forceinline__ void retention_fused(const Params& p, LAS unsigned char* lds, int unit) {
;     const int tid = threadIdx.x, lane = tid & 63, wid = __builtin_amdgcn_readfirstlane(tid >> 6), fr = lane & 15, fq = lane >> 4;
;     const int b = unit >> 5, h = (unit >> 3) & 3, vb = unit & 7;
;     unsigned char* ws = p.ws;
;     const bf16_t* Qg = (const bf16_t*)(ws + WS_Q) + (size_t)b * SEQ * D + h * 256;
;     const bf16_t* Kg = (const bf16_t*)(ws + WS_K) + (size_t)b * SEQ * D + h * 256;
;     const bf16_t* Vg = (const bf16_t*)(ws + WS_V) + (size_t)b * SEQ * VD + h * 512 + vb * 64;
;     bf16_t* Og = (bf16_t*)(ws + WS_O) + (size_t)b * SEQ * VD + h * 512 + vb * 64;
;     const float log2g = __log2f(1.0f - exp2f(-5.0f - (float)h));
;     const float gC = exp2f(128.0f * log2g);
;     f32x4 S[2][4];
; #pragma unroll
;     for (int mt = 0; mt < 2; ++mt)
; #pragma unroll
;         for (int nt = 0; nt < 4; ++nt) S[mt][nt] = (f32x4){0.f, 0.f, 0.f, 0.f};
;     LAS unsigned char* Ks = lds + LDS_KS; LAS unsigned char* Vs = lds + LDS_VS; LAS unsigned char* Vw = lds + LDS_VW; LAS unsigned char* St = lds + LDS_ST;
;     LAS f32x4* qs = (LAS f32x4*)(lds + LDS_FQ); LAS f32x4* kws = (LAS f32x4*)(lds + LDS_FK); LAS float* asc = (LAS float*)(lds + LDS_FA); LAS float* red = (LAS float*)(lds + 0);
;     const int v4 = tid & 127, rg = tid >> 7;
;     u32x2 vjp[4]; f32x4 oa[4];
;     const float* S0 = nullptr; float* S1 = nullptr; bf16_t* Ogs = nullptr;
;     float sg = 0.f, sg2 = 0.f, sg3 = 0.f, sg4 = 0.f;
; #pragma unroll
;     for (int i = 0; i < 4; ++i) { vjp[i] = (u32x2){0u, 0u}; oa[i] = (f32x4){0.f, 0.f, 0.f, 0.f}; }
.LBB0_1034:
	s_and_b64 vcc, exec, s[0:1]
	s_cbranch_vccz .LBB0_1059
	s_ashr_i32 s16, s78, 5
	s_bfe_u32 s33, s78, 0x20003
	s_ashr_i32 s17, s16, 31
	s_add_u32 s10, s74, 0xc009000
	s_addc_u32 s11, s75, 0
	s_lshl_b64 s[0:1], s[16:17], 22
	s_add_u32 s2, s10, s0
	s_addc_u32 s3, s11, s1
	s_lshl_b32 s8, s33, 9
	s_add_u32 s2, s2, s8
	s_addc_u32 s3, s3, 0
	s_lshl_b32 s4, s78, 6
	s_and_b32 s36, s4, 0x1c0
	s_add_u32 s12, s74, 0x16509000
	s_addc_u32 s13, s75, 0
	s_lshl_b64 s[4:5], s[16:17], 23
	v_cvt_f32_ubyte0_e32 v1, s33
	s_add_u32 s6, s12, s4
	v_sub_f32_e32 v1, 0xc0a00000, v1
	s_mov_b32 s15, 0xc2fc0000
	s_addc_u32 s7, s13, s5
	s_lshl_b32 s9, s33, 10
	v_mov_b32_e32 v4, 0x42800000
	v_cmp_gt_f32_e32 vcc, s15, v1
	s_add_u32 s14, s6, s9
	s_addc_u32 s18, s7, 0
	v_cndmask_b32_e32 v2, 0, v4, vcc
	v_add_f32_e32 v1, v1, v2
	v_exp_f32_e32 v1, v1
	s_and_b64 s[6:7], vcc, exec
	v_readfirstlane_b32 s22, v146
	s_cselect_b32 s6, 0xffffffc0, 0
	s_lshr_b32 s17, s22, 6
	s_add_u32 s20, s74, 0x9f09000
	s_addc_u32 s21, s75, 0
	v_ldexp_f32 v1, v1, s6
	s_add_u32 s6, s20, s0
	s_addc_u32 s7, s21, s1
	s_add_u32 s23, s74, 0xe109000
	v_sub_f32_e32 v1, 1.0, v1
	s_addc_u32 s24, s75, 0
	v_log_f32_e32 v153, v1
	s_add_u32 s0, s23, s4
	s_addc_u32 s1, s24, s5
	s_add_u32 s9, s0, s9
	s_addc_u32 s25, s1, 0
	s_lshl_b32 s26, s36, 1
	v_mul_f32_e32 v1, 0x43000000, v153
	s_add_u32 s0, s14, s26
	s_addc_u32 s1, s18, 0
	v_cmp_gt_f32_e32 vcc, s15, v1
	s_add_u32 s4, s6, s8
	s_addc_u32 s5, s7, 0
	v_cndmask_b32_e32 v1, 0, v4, vcc
	v_fmac_f32_e32 v1, 0x43000000, v153
	s_add_u32 s6, s9, s26
	v_exp_f32_e32 v1, v1
	s_addc_u32 s7, s25, 0
	v_and_b32_e32 v2, 31, v146
	s_and_b64 s[8:9], vcc, exec
	v_lshlrev_b32_e32 v118, 4, v2
	v_mov_b32_e32 v119, 0
	v_and_b32_e32 v2, 7, v146
	v_and_b32_e32 v114, 15, v146
	s_cselect_b32 s8, 0xffffffc0, 0
	v_lshl_add_u64 v[120:121], s[2:3], 0, v[118:119]
	v_add_u32_e32 v15, 0, v118
	v_lshlrev_b32_e32 v118, 4, v2
	v_lshlrev_b32_e32 v2, 3, v146
	v_ldexp_f32 v116, v1, s8
	s_and_b32 s8, s22, 0xffffffc0
	v_and_b32_e32 v18, 24, v2
	v_lshlrev_b32_e32 v2, 1, v114
	v_mov_b32_e32 v3, v119
	v_lshl_add_u64 v[126:127], s[0:1], 0, v[2:3]
	s_add_i32 s0, s8, 0
	s_add_i32 s9, 0, 0x19000
	s_add_i32 s2, 0, 0x10800
	v_add_u32_e32 v19, s0, v18
	s_and_b32 s0, s78, 3
	v_bfe_u32 v9, v146, 4, 2
	s_add_i32 s18, s9, s8
	v_add_u32_e32 v184, s2, v118
	s_add_i32 s2, 0, 0x14c00
	s_lshl_b32 s37, s17, 4
	s_lshl_b32 s1, s0, 9
	v_lshlrev_b32_e32 v1, 3, v9
	v_bfe_u32 v17, v146, 2, 2
	s_add_u32 s38, s20, s1
	v_add_u32_e32 v14, s18, v1
	v_or_b32_e32 v3, v1, v17
	s_addc_u32 s39, s21, 0
	v_cvt_f32_ubyte0_e32 v1, s0
	s_add_u32 s40, s10, s1
	v_sub_f32_e32 v1, 0xc0a00000, v1
	v_lshl_add_u64 v[122:123], s[6:7], 0, v[118:119]
	v_add_u32_e32 v185, s2, v118
	v_and_b32_e32 v118, 48, v146
	s_addc_u32 s41, s11, 0
	s_lshl_b32 s1, s0, 10
	v_cmp_gt_f32_e32 vcc, s15, v1
	v_lshl_add_u64 v[124:125], s[4:5], 0, v[118:119]
	s_add_u32 s4, s23, s1
	v_cndmask_b32_e32 v2, 0, v4, vcc
	s_addc_u32 s5, s24, 0
	v_add_f32_e32 v1, v1, v2
	s_add_u32 s42, s12, s1
	v_exp_f32_e32 v1, v1
	s_addc_u32 s43, s13, 0
	s_and_b64 s[0:1], vcc, exec
	s_cselect_b32 s0, 0xffffffc0, 0
	v_ldexp_f32 v1, v1, s0
	v_and_b32_e32 v5, 0x7f, v146
	v_sub_f32_e32 v131, 1.0, v1
	v_lshlrev_b32_e32 v1, 4, v146
	s_add_i32 s44, 0, 0x21400
	s_add_i32 s45, 0, 0x22400
	v_add_u32_e32 v187, s44, v1
	v_add_u32_e32 v188, s45, v1
	v_lshlrev_b32_e32 v10, 3, v5
	v_mov_b32_e32 v11, v119
	v_lshrrev_b32_e32 v1, 5, v146
	v_lshl_add_u64 v[136:137], s[4:5], 0, v[10:11]
	v_lshlrev_b32_e32 v191, 10, v1
	v_mul_u32_u24_e32 v11, 0x210, v1
	v_add_u32_e32 v1, 0x200, v146
	v_lshrrev_b32_e32 v12, 5, v1
	v_lshlrev_b32_e32 v192, 10, v12
	v_mul_u32_u24_e32 v21, 0x210, v12
	v_add_u32_e32 v12, 0x600, v146
	v_lshrrev_b32_e32 v12, 5, v12
	v_lshlrev_b32_e32 v194, 10, v12
	v_mul_u32_u24_e32 v22, 0x210, v12
	v_add_u32_e32 v12, 0xa00, v146
	v_lshrrev_b32_e32 v12, 5, v12
	v_lshlrev_b32_e32 v196, 10, v12
	v_mul_u32_u24_e32 v23, 0x210, v12
	v_add_u32_e32 v12, 0xe00, v146
	v_lshrrev_b32_e32 v12, 5, v12
	v_mul_f32_e32 v133, v131, v131
	v_lshlrev_b32_e32 v198, 10, v12
	v_mul_u32_u24_e32 v24, 0x210, v12
	v_lshrrev_b32_e32 v12, 3, v146
	v_lshrrev_b32_e32 v1, 3, v1
	v_mov_b32_e32 v2, v133
	v_mov_b32_e32 v130, v133
	v_lshlrev_b32_e32 v199, 11, v12
	v_mul_u32_u24_e32 v200, 0x88, v12
	v_xor_b32_e32 v12, 0x7f, v12
	v_sub_u32_e32 v13, 0x7f, v1
	v_pk_mul_f32 v[134:135], v[2:3], v[130:131] op_sel_hi:[0,1]
	v_cvt_f32_ubyte0_e32 v12, v12
	v_cvt_f32_i32_e32 v13, v13
	v_lshlrev_b32_e32 v130, 2, v9
	v_mul_f32_e32 v12, v153, v12
	v_or_b32_e32 v203, s37, v130
	v_exp_f32_e32 v140, v12
	v_or_b32_e32 v12, 1, v203
	v_cvt_f32_u32_e32 v12, v12
	v_lshlrev_b32_e32 v201, 11, v1
	v_mul_u32_u24_e32 v202, 0x88, v1
	v_mul_f32_e32 v1, v153, v13
	v_or_b32_e32 v13, 2, v203
	v_cvt_f32_u32_e32 v13, v13
	v_exp_f32_e32 v142, v1
	v_mul_f32_e32 v1, v153, v12
	v_or_b32_e32 v12, 3, v203
	v_cvt_f32_u32_e32 v12, v12
	v_exp_f32_e32 v144, v1
	v_mul_f32_e32 v1, v153, v13
	v_add_u32_e32 v13, 4, v203
	v_cvt_f32_u32_e32 v13, v13
	v_exp_f32_e32 v145, v1
	v_mul_f32_e32 v1, v153, v12
	v_exp_f32_e32 v148, v1
	v_sub_u32_e32 v1, v114, v130
	v_mul_f32_e32 v12, v153, v13
	v_cvt_f32_i32_e32 v13, v1
	v_or_b32_e32 v1, 1, v130
	v_sub_u32_e32 v25, v114, v1
	v_cvt_f32_i32_e32 v25, v25
	v_or_b32_e32 v152, 2, v130
	s_waitcnt lgkmcnt(0)
; #define LAS __attribute__((address_space(3)))
; __device__ __forceinline__ void retention_fused(const Params& p, LAS unsigned char* lds, int unit) {
;     ...
;     const float log2g = __log2f(1.0f - exp2f(-5.0f - (float)h));
;     const float gC = exp2f(128.0f * log2g);
;     f32x4 S[2][4];
; #pragma unroll
;     for (int mt = 0; mt < 2; ++mt)
; #pragma unroll
;         for (int nt = 0; nt < 4; ++nt) S[mt][nt] = (f32x4){0.f, 0.f, 0.f, 0.f};
;     LAS unsigned char* Ks = lds + LDS_KS; LAS unsigned char* Vs = lds + LDS_VS; LAS unsigned char* Vw = lds + LDS_VW; LAS unsigned char* St = lds + LDS_ST;
;     LAS f32x4* qs = (LAS f32x4*)(lds + LDS_FQ); LAS f32x4* kws = (LAS f32x4*)(lds + LDS_FK); LAS float* asc = (LAS float*)(lds + LDS_FA); LAS float* red = (LAS float*)(lds + 0);
;     const int v4 = tid & 127, rg = tid >> 7;
;     u32x2 vjp[4]; f32x4 oa[4];
;     const float* S0 = nullptr; float* S1 = nullptr; bf16_t* Ogs = nullptr;
;     float sg = 0.f, sg2 = 0.f, sg3 = 0.f, sg4 = 0.f;
; #pragma unroll
;     for (int i = 0; i < 4; ++i) { vjp[i] = (u32x2){0u, 0u}; oa[i] = (f32x4){0.f, 0.f, 0.f, 0.f}; }
	v_exp_f32_e32 v149, v12
	v_mul_f32_e32 v12, v153, v13
	v_or_b32_e32 v115, 3, v130
	v_sub_u32_e32 v13, v114, v152
	v_exp_f32_e32 v150, v12
	v_mul_f32_e32 v12, v153, v25
	v_cvt_f32_i32_e32 v13, v13
	v_sub_u32_e32 v25, v114, v115
	v_cvt_f32_i32_e32 v25, v25
	s_lshr_b32 s23, s22, 5
	s_lshr_b32 s18, s22, 7
	s_lshl_b32 s22, s22, 5
	s_and_b32 s26, s22, 0x800
	s_add_i32 s46, 0, 0x23400
	s_lshl_b32 s22, s17, 3
	v_exp_f32_e32 v151, v12
	v_mul_f32_e32 v12, v153, v13
	s_add_i32 s47, s46, s22
	s_or_b32 s22, s23, 1
	v_exp_f32_e32 v154, v12
	v_mul_f32_e32 v12, v153, v25
	v_lshrrev_b32_e32 v183, 7, v146
	v_lshlrev_b32_e32 v138, 4, v5
	s_lshl_b32 s23, s22, 10
	s_lshl_b32 s22, s22, 2
	v_exp_f32_e32 v155, v12
	v_mov_b32_e32 v139, v119
	s_mov_b32 s19, 0
	s_movk_i32 s14, 0x7f
	v_and_b32_e32 v7, 63, v146
	v_or_b32_e32 v2, 0x800, v146
	v_lshl_add_u32 v189, v183, 13, 0
	s_movk_i32 s4, 0xe800
	s_and_b32 s27, s23, 0xc00
	s_add_i32 s48, s46, s22
	v_readlane_b32 s52, v247, 0
	v_lshl_add_u64 v[12:13], s[72:73], 0, v[138:139]
	s_mov_b64 s[22:23], 0x5310000
	v_add_u32_e32 v16, s9, v118
	v_add_u32_e32 v20, s2, v18
	s_movk_i32 s0, 0x100
	v_or_b32_e32 v4, 0xc00, v146
	s_lshl_b64 s[20:21], s[18:19], 11
	v_lshlrev_b32_e32 v6, 2, v7
	v_cmp_eq_u32_e64 s[2:3], 0, v7
	v_lshlrev_b32_e32 v8, 2, v5
	v_lshlrev_b32_e32 v10, 11, v183
	v_mad_i32_i24 v5, v183, s4, v189
	s_movk_i32 s4, 0x80
	v_cmp_lt_u32_e64 s[6:7], s14, v146
	s_movk_i32 s12, 0xff
	s_movk_i32 s14, 0x17f
	s_movk_i32 s24, 0x210
	v_mul_u32_u24_e32 v7, 0x210, v114
	v_mul_u32_u24_e32 v25, 0x210, v3
	v_mul_u32_u24_e32 v3, 0x88, v3
	v_readlane_b32 s53, v247, 1
	v_readlane_b32 s54, v247, 2
	v_readlane_b32 s55, v247, 3
	v_readlane_b32 s56, v247, 4
	v_readlane_b32 s57, v247, 5
	v_readlane_b32 s58, v247, 6
	v_readlane_b32 s59, v247, 7
	v_lshl_add_u64 v[158:159], v[12:13], 0, s[22:23]
	s_lshl_b32 s50, s18, 1
	v_mul_u32_u24_e32 v9, 0x220, v9
	v_mul_u32_u24_e32 v12, 0x88, v17
	s_mov_b32 s18, s19
	v_lshlrev_b32_e32 v206, 1, v2
	v_mbcnt_lo_u32_b32 v2, -1, 0
	v_or_b32_e32 v186, s37, v114
	v_mov_b32_e32 v128, v116
	v_mov_b32_e32 v129, v116
	v_cmp_gt_u32_e64 s[0:1], s0, v146
	v_cmp_gt_u32_e64 s[4:5], s4, v146
	v_cmp_eq_u32_e64 s[8:9], 1, v183
	v_cmp_eq_u32_e64 s[10:11], 2, v183
	v_lshlrev_b32_e32 v190, 4, v183
	v_cmp_lt_u32_e64 s[12:13], s12, v146
	v_cmp_lt_u32_e64 s[14:15], s14, v146
	s_mov_b32 s49, 0x8000
	v_or_b32_e32 v193, 0x8000, v191
	v_or_b32_e32 v195, 0x10000, v191
	v_or_b32_e32 v197, 0x18000, v191
	v_lshl_add_u64 v[156:157], s[58:59], 0, v[138:139]
	v_mov_b32_e32 v141, v140
	v_mov_b32_e32 v143, v142
	v_mov_b32_e32 v132, v135
	v_mad_u32_u24 v139, v114, s24, v118
	s_add_i32 s50, s50, 2
	v_add3_u32 v204, v9, v12, v18
	v_mov_b64_e32 v[164:165], 0
	s_mov_b64 s[24:25], 0
	v_mov_b64_e32 v[168:169], s[18:19]
	s_movk_i32 s51, 0x4000
	v_lshlrev_b32_e32 v205, 1, v146
	v_lshlrev_b32_e32 v207, 1, v4
	v_lshlrev_b32_e32 v118, 1, v6
	s_lshl_b32 s18, s26, 1
	s_lshl_b32 s22, s27, 1
	s_movk_i32 s52, 0x2000
	v_add_u32_e32 v208, v14, v7
	v_add_u32_e32 v209, v15, v11
	v_add_u32_e32 v210, v15, v21
	v_add_u32_e32 v211, v15, v22
	v_add_u32_e32 v212, v15, v23
	v_add_u32_e32 v213, v15, v24
	s_movk_i32 s53, 0x6000
	v_add_u32_e32 v214, v16, v7
	s_mov_b32 s54, 0xa000
	s_mov_b32 s55, 0xc000
	s_mov_b32 s56, 0xe000
	v_add_u32_e32 v215, v19, v25
	v_add_u32_e32 v216, v20, v3
	v_add_u32_e32 v217, v5, v138
	v_lshlrev_b32_e32 v160, 1, v10
	v_lshlrev_b32_e32 v162, 1, v8
	v_mbcnt_hi_u32_b32 v218, -1, v2
	v_mov_b64_e32 v[166:167], 0
	v_mov_b32_e32 v219, v119
	v_mov_b32_e32 v220, v119
	s_mov_b32 s57, s19
	v_mov_b32_e32 v30, v119
	v_mov_b32_e32 v31, v119
	v_mov_b32_e32 v32, v119
	v_mov_b32_e32 v33, v119
	v_mov_b32_e32 v18, v119
	v_mov_b32_e32 v19, v119
	v_mov_b32_e32 v20, v119
	v_mov_b32_e32 v21, v119
; __device__ __forceinline__ unsigned cvt_pk_bf16(float lo, float hi) { const bf16x2_cv v = __builtin_convertvector((f32x2_cv){lo, hi}, bf16x2_cv); return __builtin_bit_cast(unsigned, v); }
; #define LAS __attribute__((address_space(3)))
; __device__ __forceinline__ void retention_fused(const Params& p, LAS unsigned char* lds, int unit) {
;     ...
;     f32x4 S[2][4];
; #pragma unroll
;     for (int mt = 0; mt < 2; ++mt)
; #pragma unroll
;         for (int nt = 0; nt < 4; ++nt) S[mt][nt] = (f32x4){0.f, 0.f, 0.f, 0.f};
;     LAS unsigned char* Ks = lds + LDS_KS; LAS unsigned char* Vs = lds + LDS_VS; LAS unsigned char* Vw = lds + LDS_VW; LAS unsigned char* St = lds + LDS_ST;
;     LAS f32x4* qs = (LAS f32x4*)(lds + LDS_FQ); LAS f32x4* kws = (LAS f32x4*)(lds + LDS_FK); LAS float* asc = (LAS float*)(lds + LDS_FA); LAS float* red = (LAS float*)(lds + 0);
;     const int v4 = tid & 127, rg = tid >> 7;
;     u32x2 vjp[4]; f32x4 oa[4];
;     const float* S0 = nullptr; float* S1 = nullptr; bf16_t* Ogs = nullptr;
;     float sg = 0.f, sg2 = 0.f, sg3 = 0.f, sg4 = 0.f;
; #pragma unroll
;     for (int i = 0; i < 4; ++i) { vjp[i] = (u32x2){0u, 0u}; oa[i] = (f32x4){0.f, 0.f, 0.f, 0.f}; }
;     ...
;         for (int i = 0; i < 8; ++i) { const int id = tid + i * NTHREADS, row = id >> 5, cc = id & 31; *(LAS u32x4*)(Ks + row * KS_STRIDE + cc * 16) = *(const u32x4*)(Kg + (size_t)(c * 128 + row) * D + cc * 8); }
; #pragma unroll
;         for (int i = 0; i < 2; ++i) { const int id = tid + i * NTHREADS, row = id >> 3, cc = id & 7;
;             const u32x4 v = *(const u32x4*)(Vg + (size_t)(c * 128 + row) * VD + cc * 8);
;             *(LAS u32x4*)(Vs + row * VS_STRIDE + cc * 16) = v;
;             const float sw = __builtin_amdgcn_exp2f((float)(127 - row) * log2g);
;             u32x4 w; w.x = cvt_pk_bf16(bflo(v.x) * sw, bfhi(v.x) * sw); w.y = cvt_pk_bf16(bflo(v.y) * sw, bfhi(v.y) * sw); w.z = cvt_pk_bf16(bflo(v.z) * sw, bfhi(v.z) * sw); w.w = cvt_pk_bf16(bflo(v.w) * sw, bfhi(v.w) * sw);
;             *(LAS u32x4*)(Vw + row * VS_STRIDE + cc * 16) = w; }
;         bf16x8 qf[8];
; #pragma unroll
;         for (int ks = 0; ks < 8; ++ks) qf[ks] = *(const bf16x8*)(Qg + (size_t)(c * 128 + 16 * wid + fr) * D + ks * 32 + fq * 8);
	v_mov_b32_e32 v22, v119
	v_mov_b32_e32 v23, v119
	v_mov_b32_e32 v24, v119
	v_mov_b32_e32 v25, v119
	v_mov_b32_e32 v26, v119
	v_mov_b32_e32 v27, v119
	v_mov_b32_e32 v28, v119
	v_mov_b32_e32 v29, v119
	v_mov_b32_e32 v2, v119
	v_mov_b32_e32 v3, v119
	v_mov_b32_e32 v4, v119
	v_mov_b32_e32 v5, v119
	v_mov_b32_e32 v6, v119
	v_mov_b32_e32 v7, v119
	v_mov_b32_e32 v8, v119
	v_mov_b32_e32 v9, v119
	v_mov_b32_e32 v10, v119
	v_mov_b32_e32 v11, v119
	v_mov_b32_e32 v12, v119
	v_mov_b32_e32 v13, v119
	v_mov_b32_e32 v14, v119
	v_mov_b32_e32 v15, v119
	v_mov_b32_e32 v16, v119
	v_mov_b32_e32 v17, v119
	v_mov_b32_e32 v34, v119
	v_mov_b32_e32 v35, v119
	v_mov_b32_e32 v36, v119
	v_mov_b32_e32 v37, v119
	v_mov_b32_e32 v38, v119
	v_mov_b32_e32 v39, v119
	v_mov_b32_e32 v40, v119
	v_mov_b32_e32 v41, v119
	v_mov_b32_e32 v42, v119
	v_mov_b32_e32 v43, v119
	v_mov_b32_e32 v44, v119
	v_mov_b32_e32 v45, v119
	v_mov_b32_e32 v46, v119
	v_mov_b32_e32 v47, v119
	v_mov_b32_e32 v48, v119
	v_mov_b32_e32 v49, v119
	v_mov_b32_e32 v170, v119
	v_mov_b32_e32 v171, v119
	v_mov_b32_e32 v172, v119
	v_mov_b32_e32 v173, v119
	v_mov_b32_e32 v174, v119
	v_mov_b32_e32 v175, v119
	v_mov_b32_e32 v176, v119
	v_mov_b32_e32 v177, v119
	v_readlane_b32 s60, v247, 8
	v_readlane_b32 s61, v247, 9
	v_readlane_b32 s62, v247, 10
	v_readlane_b32 s63, v247, 11
	v_readlane_b32 s64, v247, 12
	v_readlane_b32 s65, v247, 13
	v_readlane_b32 s66, v247, 14
	v_readlane_b32 s67, v247, 15
	s_lshl_b32 s23, s57, 17
	v_or_b32_e32 v50, s23, v191
	v_or_b32_e32 v52, s23, v192
	v_or_b32_e32 v58, s23, v193
	v_or_b32_e32 v60, s23, v194
	v_lshlrev_b32_e32 v50, 1, v50
	v_mov_b32_e32 v51, v119
	v_lshlrev_b32_e32 v52, 1, v52
	v_mov_b32_e32 v53, v119
	v_lshlrev_b32_e32 v58, 1, v58
	v_mov_b32_e32 v59, v119
	v_lshlrev_b32_e32 v60, 1, v60
	v_mov_b32_e32 v61, v119
	v_lshl_add_u64 v[50:51], v[120:121], 0, v[50:51]
	v_lshl_add_u64 v[54:55], v[120:121], 0, v[52:53]
	v_lshl_add_u64 v[58:59], v[120:121], 0, v[58:59]
	v_lshl_add_u64 v[62:63], v[120:121], 0, v[60:61]
	global_load_dwordx4 v[50:53], v[50:51], off
	s_nop 0
	global_load_dwordx4 v[54:57], v[54:55], off
	s_nop 0
	global_load_dwordx4 v[58:61], v[58:59], off
	s_nop 0
	global_load_dwordx4 v[62:65], v[62:63], off
	v_or_b32_e32 v66, s23, v195
	v_or_b32_e32 v68, s23, v196
	v_lshlrev_b32_e32 v66, 1, v66
	v_mov_b32_e32 v67, v119
	v_lshlrev_b32_e32 v68, 1, v68
	v_mov_b32_e32 v69, v119
	v_or_b32_e32 v74, s23, v197
	v_lshl_add_u64 v[66:67], v[120:121], 0, v[66:67]
	v_lshl_add_u64 v[70:71], v[120:121], 0, v[68:69]
	v_lshlrev_b32_e32 v74, 1, v74
	v_mov_b32_e32 v75, v119
	v_add_lshl_u32 v76, s23, v198, 1
	v_mov_b32_e32 v77, v119
	global_load_dwordx4 v[66:69], v[66:67], off
	s_nop 0
	global_load_dwordx4 v[70:73], v[70:71], off
	v_lshl_add_u64 v[74:75], v[120:121], 0, v[74:75]
	v_lshl_add_u64 v[78:79], v[120:121], 0, v[76:77]
	global_load_dwordx4 v[74:77], v[74:75], off
	s_nop 0
	global_load_dwordx4 v[78:81], v[78:79], off
	s_lshl_b32 s23, s57, 18
	v_or_b32_e32 v82, s23, v199
	v_lshlrev_b32_e32 v82, 1, v82
	v_mov_b32_e32 v83, v119
	v_lshl_add_u64 v[82:83], v[122:123], 0, v[82:83]
	global_load_dwordx4 v[178:181], v[82:83], off
	v_add_lshl_u32 v82, s23, v201, 1
	v_mov_b32_e32 v83, v119
	v_lshl_add_u64 v[82:83], v[122:123], 0, v[82:83]
	global_load_dwordx4 v[222:225], v[82:83], off
	s_lshl_b32 s23, s57, 7
	v_mov_b32_e32 v83, v119
	v_add_u32_e32 v82, s23, v186
	v_lshlrev_b64 v[82:83], 11, v[82:83]
	v_lshl_add_u64 v[110:111], v[124:125], 0, v[82:83]
	global_load_dwordx4 v[82:85], v[110:111], off
	global_load_dwordx4 v[86:89], v[110:111], off offset:64
	global_load_dwordx4 v[90:93], v[110:111], off offset:128
	global_load_dwordx4 v[94:97], v[110:111], off offset:192
	global_load_dwordx4 v[98:101], v[110:111], off offset:256
	s_branch .LBB0_1038
